# final LayerNorm output stores without the nt hint (the output may stay in the memory-side cache), on top of the pipelined mem conversion
# baseline (speedup 1.0000x reference)
; __device__ __forceinline__ float bflo(unsigned u) { return __uint_as_float(u << 16); }
; __device__ __forceinline__ float bfhi(unsigned u) { return __uint_as_float(u & 0xffff0000u); }
; __device__ void ln_phase2(const bf16_t* __restrict__ mix, const float* __restrict__ Rf, const bf16_t* __restrict__ Rb, const float* __restrict__ gam, const float* __restrict__ bet, bf16_t* ob, float* of) {
;     ...
;     for (int row = blockIdx.x * 8 + wid; row < T_TOK; row += gridDim.x * 8) {
;         const size_t ro = (size_t)row * DM + lane * 8;
;         float v[32]; float s = 0.f;
; #pragma unroll
;         for (int j = 0; j < 4; ++j) {
;             const u32x4 m = *(const u32x4*)(mix + ro + 512 * j);
;             float r[8];
;             if (Rf) { const f32x4 a = *(const f32x4*)(Rf + ro + 512 * j), b = *(const f32x4*)(Rf + ro + 512 * j + 4);
;                 r[0] = a[0]; r[1] = a[1]; r[2] = a[2]; r[3] = a[3]; r[4] = b[0]; r[5] = b[1]; r[6] = b[2]; r[7] = b[3]; }
;             else { const u32x4 rb = *(const u32x4*)(Rb + ro + 512 * j);
;                 r[0] = bflo(rb.x); r[1] = bfhi(rb.x); r[2] = bflo(rb.y); r[3] = bfhi(rb.y); r[4] = bflo(rb.z); r[5] = bfhi(rb.z); r[6] = bflo(rb.w); r[7] = bfhi(rb.w); }
;             v[8 * j + 0] = DN_ALPHA * r[0] + bflo(m.x); v[8 * j + 1] = DN_ALPHA * r[1] + bfhi(m.x); v[8 * j + 2] = DN_ALPHA * r[2] + bflo(m.y); v[8 * j + 3] = DN_ALPHA * r[3] + bfhi(m.y);
;             v[8 * j + 4] = DN_ALPHA * r[4] + bflo(m.z); v[8 * j + 5] = DN_ALPHA * r[5] + bfhi(m.z); v[8 * j + 6] = DN_ALPHA * r[6] + bflo(m.w); v[8 * j + 7] = DN_ALPHA * r[7] + bfhi(m.w);
; #pragma unroll
;             for (int e = 0; e < 8; ++e) s += v[8 * j + e];
;         }
; #pragma unroll
;         for (int o = 32; o; o >>= 1) s += __shfl_xor(s, o);
;         const float mean = s * (1.0f / 2048.0f);
.LBB0_31:
	v_ashrrev_i32_e32 v1, 31, v0
	v_lshlrev_b64 v[88:89], 11, v[0:1]
	v_or_b32_e32 v88, v88, v84
	v_lshlrev_b64 v[68:69], 1, v[88:89]
	v_lshl_add_u64 v[70:71], s[68:69], 0, v[68:69]
	v_lshl_add_u64 v[72:73], s[92:93], 0, v[68:69]
	global_load_dwordx4 v[94:97], v[70:71], off nt
	global_load_dwordx4 v[98:101], v[72:73], off nt
	global_load_dwordx4 v[110:113], v[70:71], off offset:1024 nt
	global_load_dwordx4 v[114:117], v[72:73], off offset:1024 nt
	global_load_dwordx4 v[76:79], v[70:71], off offset:2048 nt
	global_load_dwordx4 v[80:83], v[72:73], off offset:2048 nt
	s_nop 0
	global_load_dwordx4 v[68:71], v[70:71], off offset:3072 nt
	s_nop 0
	global_load_dwordx4 v[72:75], v[72:73], off offset:3072 nt
	v_add_u32_e32 v0, s10, v0
	s_waitcnt vmcnt(0)
	v_lshlrev_b32_e32 v92, 16, v97
	v_and_b32_e32 v93, 0xffff0000, v97
	v_and_b32_e32 v97, 0xffff0000, v94
	s_waitcnt vmcnt(5)
	v_lshlrev_b32_e32 v102, 16, v110
	v_and_b32_e32 v103, 0xffff0000, v110
	v_lshlrev_b32_e32 v104, 16, v111
	s_waitcnt vmcnt(1)
	v_and_b32_e32 v90, 0xffff0000, v70
	s_waitcnt vmcnt(0)
	v_and_b32_e32 v86, 0xffff0000, v74
	v_lshlrev_b32_e32 v87, 16, v74
	v_lshlrev_b32_e32 v91, 16, v70
	v_and_b32_e32 v74, 0xffff0000, v75
	v_lshlrev_b32_e32 v75, 16, v75
	v_and_b32_e32 v70, 0xffff0000, v71
	v_lshlrev_b32_e32 v71, 16, v71
	v_pk_fma_f32 v[86:87], v[86:87], s[4:5], v[90:91] op_sel_hi:[1,0,1]
	v_pk_fma_f32 v[74:75], v[74:75], s[4:5], v[70:71] op_sel_hi:[1,0,1]
	v_lshl_add_u64 v[70:71], v[88:89], 2, s[90:91]
	v_lshlrev_b32_e32 v88, 16, v100
	v_and_b32_e32 v89, 0xffff0000, v100
	v_lshlrev_b32_e32 v90, 16, v96
	v_and_b32_e32 v91, 0xffff0000, v96
	v_pk_fma_f32 v[88:89], v[88:89], s[4:5], v[90:91] op_sel_hi:[1,0,1]
	v_lshlrev_b32_e32 v90, 16, v101
	v_and_b32_e32 v91, 0xffff0000, v101
	v_pk_fma_f32 v[90:91], v[90:91], s[4:5], v[92:93] op_sel_hi:[1,0,1]
	v_lshlrev_b32_e32 v92, 16, v98
	v_and_b32_e32 v93, 0xffff0000, v98
	v_lshlrev_b32_e32 v96, 16, v94
	v_pk_fma_f32 v[92:93], v[92:93], s[4:5], v[96:97] op_sel_hi:[1,0,1]
	v_lshlrev_b32_e32 v96, 16, v99
	v_add_f32_e32 v1, 0, v92
	v_and_b32_e32 v97, 0xffff0000, v99
	v_lshlrev_b32_e32 v94, 16, v95
	v_and_b32_e32 v95, 0xffff0000, v95
	v_add_f32_e32 v1, v93, v1
	v_pk_fma_f32 v[94:95], v[96:97], s[4:5], v[94:95] op_sel_hi:[1,0,1]
	v_lshlrev_b32_e32 v96, 16, v116
	v_add_f32_e32 v1, v94, v1
	v_add_f32_e32 v1, v95, v1
	v_add_f32_e32 v1, v88, v1
	v_and_b32_e32 v97, 0xffff0000, v116
	v_lshlrev_b32_e32 v98, 16, v112
	v_and_b32_e32 v99, 0xffff0000, v112
	v_add_f32_e32 v1, v89, v1
	v_pk_fma_f32 v[96:97], v[96:97], s[4:5], v[98:99] op_sel_hi:[1,0,1]
	v_lshlrev_b32_e32 v98, 16, v117
	v_and_b32_e32 v99, 0xffff0000, v117
	v_lshlrev_b32_e32 v100, 16, v113
	v_and_b32_e32 v101, 0xffff0000, v113
	v_add_f32_e32 v1, v90, v1
	v_pk_fma_f32 v[98:99], v[98:99], s[4:5], v[100:101] op_sel_hi:[1,0,1]
	v_lshlrev_b32_e32 v100, 16, v114
	v_and_b32_e32 v101, 0xffff0000, v114
	v_add_f32_e32 v1, v91, v1
	v_pk_fma_f32 v[102:103], v[100:101], s[4:5], v[102:103] op_sel_hi:[1,0,1]
	v_lshlrev_b32_e32 v100, 16, v115
	v_add_f32_e32 v1, v102, v1
	v_and_b32_e32 v101, 0xffff0000, v115
	v_and_b32_e32 v105, 0xffff0000, v111
	v_add_f32_e32 v1, v103, v1
	v_pk_fma_f32 v[104:105], v[100:101], s[4:5], v[104:105] op_sel_hi:[1,0,1]
	v_lshlrev_b32_e32 v100, 16, v82
	v_add_f32_e32 v1, v104, v1
	v_add_f32_e32 v1, v105, v1
	v_add_f32_e32 v1, v96, v1
	v_add_f32_e32 v1, v97, v1
	v_and_b32_e32 v101, 0xffff0000, v82
	v_lshlrev_b32_e32 v110, 16, v78
	v_and_b32_e32 v111, 0xffff0000, v78
	v_lshlrev_b32_e32 v82, 16, v83
	v_and_b32_e32 v83, 0xffff0000, v83
	v_lshlrev_b32_e32 v78, 16, v79
	v_and_b32_e32 v79, 0xffff0000, v79
	v_add_f32_e32 v1, v98, v1
	v_pk_fma_f32 v[100:101], v[100:101], s[4:5], v[110:111] op_sel_hi:[1,0,1]
	v_pk_fma_f32 v[78:79], v[82:83], s[4:5], v[78:79] op_sel_hi:[1,0,1]
	v_lshlrev_b32_e32 v82, 16, v80
	v_and_b32_e32 v83, 0xffff0000, v80
	v_lshlrev_b32_e32 v110, 16, v76
	v_and_b32_e32 v111, 0xffff0000, v76
	v_add_f32_e32 v1, v99, v1
	v_pk_fma_f32 v[82:83], v[82:83], s[4:5], v[110:111] op_sel_hi:[1,0,1]
	v_lshlrev_b32_e32 v80, 16, v81
	v_add_f32_e32 v1, v82, v1
	v_and_b32_e32 v81, 0xffff0000, v81
	v_lshlrev_b32_e32 v76, 16, v77
	v_and_b32_e32 v77, 0xffff0000, v77
	v_add_f32_e32 v1, v83, v1
	v_pk_fma_f32 v[76:77], v[80:81], s[4:5], v[76:77] op_sel_hi:[1,0,1]
	v_lshlrev_b32_e32 v80, 16, v72
	v_add_f32_e32 v1, v76, v1
	v_add_f32_e32 v1, v77, v1
	v_add_f32_e32 v1, v100, v1
	v_add_f32_e32 v1, v101, v1
	v_add_f32_e32 v1, v78, v1
	v_and_b32_e32 v81, 0xffff0000, v72
	v_lshlrev_b32_e32 v110, 16, v68
	v_and_b32_e32 v111, 0xffff0000, v68
	v_add_f32_e32 v1, v79, v1
	v_pk_fma_f32 v[80:81], v[80:81], s[4:5], v[110:111] op_sel_hi:[1,0,1]
	v_lshlrev_b32_e32 v72, 16, v73
	v_add_f32_e32 v1, v80, v1
	v_and_b32_e32 v73, 0xffff0000, v73
	v_lshlrev_b32_e32 v68, 16, v69
	v_and_b32_e32 v69, 0xffff0000, v69
	v_add_f32_e32 v1, v81, v1
	v_pk_fma_f32 v[68:69], v[72:73], s[4:5], v[68:69] op_sel_hi:[1,0,1]
	s_nop 0
	v_add_f32_e32 v1, v68, v1
	v_add_f32_e32 v1, v69, v1
	v_add_f32_e32 v1, v87, v1
	v_add_f32_e32 v1, v86, v1
	v_add_f32_e32 v1, v75, v1
	v_add_f32_e32 v1, v74, v1
	v_mov_b32_e32 v72, v1
	s_nop 1
	v_permlane32_swap_b32 v72, v1
	v_add_f32_e32 v1, v1, v72
	v_mov_b32_e32 v72, v1
	s_nop 1
	v_permlane16_swap_b32 v72, v1
	v_add_f32_e32 v1, v1, v72
	s_nop 1
	v_add_f32_dpp v1, v1, v1 quad_perm:[1,0,3,2] row_mask:0xf bank_mask:0xf
	s_nop 1
	v_add_f32_dpp v1, v1, v1 quad_perm:[2,3,0,1] row_mask:0xf bank_mask:0xf
	s_nop 1
	v_add_f32_dpp v1, v1, v1 row_half_mirror row_mask:0xf bank_mask:0xf
	s_nop 1
	v_add_f32_dpp v1, v1, v1 row_mirror row_mask:0xf bank_mask:0xf
	v_mul_f32_e32 v72, 0x3a000000, v1
; __device__ __forceinline__ unsigned cvt_pk_bf16(float lo, float hi) { const f32x2v v = {lo, hi}; const b16x2v r = __builtin_convertvector(v, b16x2v); return __builtin_bit_cast(unsigned, r); }
; __device__ void ln_phase2(const bf16_t* __restrict__ mix, const float* __restrict__ Rf, const bf16_t* __restrict__ Rb, const float* __restrict__ gam, const float* __restrict__ bet, bf16_t* ob, float* of) {
;     ...
;         float q = 0.f;
; #pragma unroll
;         for (int e = 0; e < 32; ++e) { const float dlt = v[e] - mean; q += dlt * dlt; }
; #pragma unroll
;         for (int o = 32; o; o >>= 1) q += __shfl_xor(q, o);
;         const float rstd = rsqrtf(q * (1.0f / 2048.0f) + 1e-5f);
; #pragma unroll
;         for (int j = 0; j < 4; ++j) {
;             const f32x4 g0 = *(const f32x4*)(gam + lane * 8 + 512 * j), g1 = *(const f32x4*)(gam + lane * 8 + 512 * j + 4);
;             const f32x4 b0 = *(const f32x4*)(bet + lane * 8 + 512 * j), b1 = *(const f32x4*)(bet + lane * 8 + 512 * j + 4);
;             f32x4 y0, y1;
; #pragma unroll
;             for (int e = 0; e < 4; ++e) { y0[e] = (v[8 * j + e] - mean) * rstd * g0[e] + b0[e]; y1[e] = (v[8 * j + 4 + e] - mean) * rstd * g1[e] + b1[e]; }
;             if (ob) { u32x4 w; w.x = cvt_pk_bf16(y0[0], y0[1]); w.y = cvt_pk_bf16(y0[2], y0[3]); w.z = cvt_pk_bf16(y1[0], y1[1]); w.w = cvt_pk_bf16(y1[2], y1[3]); *(u32x4*)(ob + ro + 512 * j) = w; }
;             else { *(f32x4*)(of + ro + 512 * j) = y0; *(f32x4*)(of + ro + 512 * j + 4) = y1; }
;         }
	v_pk_add_f32 v[92:93], v[92:93], v[72:73] op_sel_hi:[1,0] neg_lo:[0,1] neg_hi:[0,1]
	v_pk_add_f32 v[94:95], v[94:95], v[72:73] op_sel_hi:[1,0] neg_lo:[0,1] neg_hi:[0,1]
	v_pk_mul_f32 v[110:111], v[92:93], v[92:93]
	v_pk_mul_f32 v[112:113], v[94:95], v[94:95]
	v_add_f32_e32 v1, v110, v111
	v_pk_add_f32 v[88:89], v[88:89], v[72:73] op_sel_hi:[1,0] neg_lo:[0,1] neg_hi:[0,1]
	v_add_f32_e32 v1, v112, v1
	v_pk_mul_f32 v[114:115], v[88:89], v[88:89]
	v_add_f32_e32 v1, v113, v1
	v_pk_add_f32 v[90:91], v[90:91], v[72:73] op_sel_hi:[1,0] neg_lo:[0,1] neg_hi:[0,1]
	v_add_f32_e32 v1, v114, v1
	v_pk_mul_f32 v[116:117], v[90:91], v[90:91]
	v_add_f32_e32 v1, v115, v1
	v_pk_add_f32 v[102:103], v[102:103], v[72:73] op_sel_hi:[1,0] neg_lo:[0,1] neg_hi:[0,1]
	v_add_f32_e32 v1, v116, v1
	v_pk_mul_f32 v[118:119], v[102:103], v[102:103]
	v_add_f32_e32 v1, v117, v1
	v_pk_add_f32 v[104:105], v[104:105], v[72:73] op_sel_hi:[1,0] neg_lo:[0,1] neg_hi:[0,1]
	v_add_f32_e32 v1, v118, v1
	v_pk_mul_f32 v[120:121], v[104:105], v[104:105]
	v_add_f32_e32 v1, v119, v1
	v_pk_add_f32 v[96:97], v[96:97], v[72:73] op_sel_hi:[1,0] neg_lo:[0,1] neg_hi:[0,1]
	v_add_f32_e32 v1, v120, v1
	v_pk_mul_f32 v[122:123], v[96:97], v[96:97]
	v_add_f32_e32 v1, v121, v1
	v_pk_add_f32 v[98:99], v[98:99], v[72:73] op_sel_hi:[1,0] neg_lo:[0,1] neg_hi:[0,1]
	v_add_f32_e32 v1, v122, v1
	v_pk_mul_f32 v[124:125], v[98:99], v[98:99]
	v_add_f32_e32 v1, v123, v1
	v_pk_add_f32 v[82:83], v[82:83], v[72:73] op_sel_hi:[1,0] neg_lo:[0,1] neg_hi:[0,1]
	v_add_f32_e32 v1, v124, v1
	v_pk_mul_f32 v[126:127], v[82:83], v[82:83]
	v_add_f32_e32 v1, v125, v1
	v_pk_add_f32 v[128:129], v[76:77], v[72:73] op_sel_hi:[1,0] neg_lo:[0,1] neg_hi:[0,1]
	v_add_f32_e32 v1, v126, v1
	v_pk_mul_f32 v[76:77], v[128:129], v[128:129]
	v_add_f32_e32 v1, v127, v1
	v_pk_add_f32 v[100:101], v[100:101], v[72:73] op_sel_hi:[1,0] neg_lo:[0,1] neg_hi:[0,1]
	v_add_f32_e32 v1, v76, v1
	v_pk_mul_f32 v[130:131], v[100:101], v[100:101]
	v_add_f32_e32 v1, v77, v1
	v_pk_add_f32 v[132:133], v[78:79], v[72:73] op_sel_hi:[1,0] neg_lo:[0,1] neg_hi:[0,1]
	v_add_f32_e32 v1, v130, v1
	v_pk_mul_f32 v[78:79], v[132:133], v[132:133]
	v_add_f32_e32 v1, v131, v1
	v_pk_add_f32 v[80:81], v[80:81], v[72:73] op_sel_hi:[1,0] neg_lo:[0,1] neg_hi:[0,1]
	v_add_f32_e32 v1, v78, v1
	v_pk_mul_f32 v[134:135], v[80:81], v[80:81]
	v_add_f32_e32 v1, v79, v1
	v_pk_add_f32 v[136:137], v[68:69], v[72:73] op_sel_hi:[1,0] neg_lo:[0,1] neg_hi:[0,1]
	v_add_f32_e32 v1, v134, v1
	v_pk_mul_f32 v[68:69], v[136:137], v[136:137]
	v_add_f32_e32 v1, v135, v1
	v_pk_add_f32 v[86:87], v[86:87], v[72:73] op_sel_hi:[1,0] neg_lo:[0,1] neg_hi:[0,1]
	v_add_f32_e32 v1, v68, v1
	v_pk_mul_f32 v[138:139], v[86:87], v[86:87]
	v_add_f32_e32 v1, v69, v1
	v_pk_add_f32 v[140:141], v[74:75], v[72:73] op_sel_hi:[1,0] neg_lo:[0,1] neg_hi:[0,1]
	v_add_f32_e32 v1, v139, v1
	v_pk_mul_f32 v[72:73], v[140:141], v[140:141]
	v_add_f32_e32 v1, v138, v1
	v_add_f32_e32 v1, v73, v1
	v_add_f32_e32 v1, v72, v1
	v_mov_b32_e32 v68, v1
	s_nop 1
	v_permlane32_swap_b32 v68, v1
	v_add_f32_e32 v1, v1, v68
	v_mov_b32_e32 v68, v1
	s_nop 1
	v_permlane16_swap_b32 v68, v1
	v_add_f32_e32 v1, v1, v68
	s_nop 1
	v_add_f32_dpp v1, v1, v1 quad_perm:[1,0,3,2] row_mask:0xf bank_mask:0xf
	s_nop 1
	v_add_f32_dpp v1, v1, v1 quad_perm:[2,3,0,1] row_mask:0xf bank_mask:0xf
	s_nop 1
	v_add_f32_dpp v1, v1, v1 row_half_mirror row_mask:0xf bank_mask:0xf
	s_nop 1
	v_add_f32_dpp v1, v1, v1 row_mirror row_mask:0xf bank_mask:0xf
	v_fmamk_f32 v1, v1, 0x3a000000, v213
	v_cmp_gt_f32_e32 vcc, s12, v1
	v_mul_f32_e32 v68, 0x4b800000, v1
	s_nop 0
	v_cndmask_b32_e32 v1, v1, v68, vcc
	v_rsq_f32_e32 v1, v1
	s_nop 0
	v_mul_f32_e32 v68, 0x45800000, v1
	v_cndmask_b32_e32 v110, v1, v68, vcc
	v_pk_mul_f32 v[68:69], v[92:93], v[110:111] op_sel_hi:[1,0]
	v_pk_mul_f32 v[72:73], v[94:95], v[110:111] op_sel_hi:[1,0]
	v_pk_mul_f32 v[76:77], v[90:91], v[110:111] op_sel_hi:[1,0]
	v_pk_fma_f32 v[74:75], v[10:11], v[72:73], v[18:19]
	v_pk_fma_f32 v[72:73], v[8:9], v[68:69], v[16:17]
	v_pk_mul_f32 v[68:69], v[88:89], v[110:111] op_sel_hi:[1,0]
	v_pk_fma_f32 v[78:79], v[6:7], v[76:77], v[14:15]
	v_pk_fma_f32 v[76:77], v[4:5], v[68:69], v[12:13]
	global_store_dwordx4 v[70:71], v[72:75], off
	global_store_dwordx4 v[70:71], v[76:79], off offset:16
	v_pk_mul_f32 v[68:69], v[102:103], v[110:111] op_sel_hi:[1,0]
	v_pk_mul_f32 v[72:73], v[104:105], v[110:111] op_sel_hi:[1,0]
	v_pk_mul_f32 v[76:77], v[98:99], v[110:111] op_sel_hi:[1,0]
	v_pk_fma_f32 v[74:75], v[26:27], v[72:73], v[34:35]
	v_pk_fma_f32 v[72:73], v[24:25], v[68:69], v[32:33]
	v_pk_mul_f32 v[68:69], v[96:97], v[110:111] op_sel_hi:[1,0]
	v_pk_fma_f32 v[78:79], v[22:23], v[76:77], v[30:31]
	v_pk_fma_f32 v[76:77], v[20:21], v[68:69], v[28:29]
	global_store_dwordx4 v[70:71], v[72:75], off offset:2048
	global_store_dwordx4 v[70:71], v[76:79], off offset:2064
	v_pk_mul_f32 v[68:69], v[82:83], v[110:111] op_sel_hi:[1,0]
	v_pk_mul_f32 v[72:73], v[128:129], v[110:111] op_sel_hi:[1,0]
	v_add_co_u32_e32 v82, vcc, s11, v70
	v_pk_fma_f32 v[74:75], v[38:39], v[72:73], v[46:47]
	v_pk_fma_f32 v[72:73], v[36:37], v[68:69], v[44:45]
	v_pk_mul_f32 v[68:69], v[100:101], v[110:111] op_sel_hi:[1,0]
	v_pk_mul_f32 v[76:77], v[132:133], v[110:111] op_sel_hi:[1,0]
	v_addc_co_u32_e32 v83, vcc, 0, v71, vcc
	v_pk_fma_f32 v[78:79], v[42:43], v[76:77], v[50:51]
	v_pk_fma_f32 v[76:77], v[40:41], v[68:69], v[48:49]
	global_store_dwordx4 v[82:83], v[72:75], off
	global_store_dwordx4 v[82:83], v[76:79], off offset:16
	v_cmp_lt_i32_e32 vcc, s13, v0
	v_pk_mul_f32 v[72:73], v[80:81], v[110:111] op_sel_hi:[1,0]
	v_pk_mul_f32 v[74:75], v[136:137], v[110:111] op_sel_hi:[1,0]
	v_pk_mul_f32 v[68:69], v[86:87], v[110:111] op_sel_hi:[1,0]
	v_pk_mul_f32 v[70:71], v[140:141], v[110:111] op_sel_hi:[1,0]
	v_pk_fma_f32 v[74:75], v[54:55], v[74:75], v[62:63]
	v_pk_fma_f32 v[72:73], v[52:53], v[72:73], v[60:61]
	s_or_b64 s[2:3], vcc, s[2:3]
	v_pk_fma_f32 v[68:69], v[56:57], v[68:69], v[64:65] op_sel:[0,1,0] op_sel_hi:[1,0,1]
	v_pk_fma_f32 v[70:71], v[58:59], v[70:71], v[66:67] op_sel:[0,1,0] op_sel_hi:[1,0,1]
	global_store_dwordx4 v[82:83], v[72:75], off offset:2048
	global_store_dwordx4 v[82:83], v[68:71], off offset:2064
	s_andn2_b64 exec, exec, s[2:3]
	s_cbranch_execnz .LBB0_31
